# counted waits: PC epilogue first gate batch awaited per load at first use (conservative counts vmcnt 7..0, stores not credited)
# speedup vs baseline: 1.0007x; 1.0007x over previous
; __device__ __forceinline__ unsigned cvt_pk_bf16(float lo, float hi) { f32x2c v = {lo, hi}; bf16x2c b = __builtin_convertvector(v, bf16x2c); return __builtin_bit_cast(unsigned, b); }
; __device__ __forceinline__ float bf_lo(unsigned w) { return __uint_as_float(w << 16); }
; __device__ __forceinline__ float bf_hi(unsigned w) { return __uint_as_float(w & 0xffff0000u); }
;     __device__ __forceinline__ void operator()(f32x4 (&acc)[2][2][4][2], const Unit& u, int wr, int wc, int fr, int fq) const {
;         const int row0 = u.pm * BM + wr * 64 + fr, col0 = u.pn * BM + wc * 32 + 8 * fq;
;         const int gcol = (u.seg == 0 ? 1280 : 2304) + col0;
; #pragma unroll
;         for (int ai = 0; ai < 2; ++ai) {
;             u32x4 ga[4][2];
; #pragma unroll
;             for (int m = 0; m < 4; ++m)
; #pragma unroll
;                 for (int bj = 0; bj < 2; ++bj) ga[m][bj] = *(const u32x4*)(P + (size_t)(row0 + ai * HALF + m * 16) * 3328 + gcol + bj * HALF);
; #pragma unroll
;             for (int m = 0; m < 4; ++m)
; #pragma unroll
;                 for (int bj = 0; bj < 2; ++bj) {
;                     const u32x4 g = ga[m][bj];
;                     const f32x4 a0 = (f32x4){bf_lo(g.x), bf_hi(g.x), bf_lo(g.y), bf_hi(g.y)}, a1 = (f32x4){bf_lo(g.z), bf_hi(g.z), bf_lo(g.w), bf_hi(g.w)};
;                     acc[ai][bj][m][0] *= a0; acc[ai][bj][m][1] *= a1;
;                     if (u.seg != 0) {
;                         const f32x4 v0 = acc[ai][bj][m][0], v1 = acc[ai][bj][m][1];
;                         u32x4 w; w.x = cvt_pk_bf16(v0[0], v0[1]); w.y = cvt_pk_bf16(v0[2], v0[3]); w.z = cvt_pk_bf16(v1[0], v1[1]); w.w = cvt_pk_bf16(v1[2], v1[3]);
;                         *(u32x4*)(O + (size_t)(row0 + ai * HALF + m * 16) * 1024 + col0 + bj * HALF) = w;
;                     }
;                 }
.LBB0_519:
	s_cmp_lg_u32 s27, 0
	s_cselect_b64 s[72:73], -1, 0
	s_cmp_eq_u32 s27, 0
	v_lshl_add_u32 v178, s29, 8, v67
	v_lshl_or_b32 v176, s28, 8, v191
	s_cselect_b64 s[28:29], -1, 0
	s_and_b64 vcc, s[28:29], exec
	s_movk_i32 s27, 0x900
	s_cselect_b32 s27, 0x500, s27
	v_add_u32_e32 v132, s27, v176
	v_ashrrev_i32_e32 v133, 31, v132
	v_lshl_add_u64 v[180:181], v[132:133], 1, s[94:95]
	v_mad_i64_i32 v[132:133], s[28:29], v178, s82, v[180:181]
	v_or_b32_e32 v186, 16, v178
	global_load_dwordx4 v[204:207], v[132:133], off
	global_load_dwordx4 v[156:159], v[132:133], off offset:256
	v_mad_i64_i32 v[132:133], s[28:29], v186, s82, v[180:181]
	v_or_b32_e32 v184, 32, v178
	global_load_dwordx4 v[152:155], v[132:133], off
	global_load_dwordx4 v[148:151], v[132:133], off offset:256
	v_mad_i64_i32 v[132:133], s[28:29], v184, s82, v[180:181]
	v_or_b32_e32 v182, 48, v178
	global_load_dwordx4 v[144:147], v[132:133], off
	global_load_dwordx4 v[140:143], v[132:133], off offset:256
	v_mad_i64_i32 v[132:133], s[28:29], v182, s82, v[180:181]
	global_load_dwordx4 v[136:139], v[132:133], off
	s_nop 0
	global_load_dwordx4 v[132:135], v[132:133], off offset:256
	v_ashrrev_i32_e32 v179, 31, v178
	v_lshlrev_b64 v[188:189], 11, v[178:179]
	v_ashrrev_i32_e32 v177, 31, v176
	v_lshl_add_u64 v[188:189], s[86:87], 0, v[188:189]
	v_lshl_add_u64 v[188:189], v[176:177], 1, v[188:189]
	s_waitcnt vmcnt(7)
	v_lshlrev_b32_e32 v208, 16, v204
	v_and_b32_e32 v209, 0xffff0000, v204
	v_lshlrev_b32_e32 v204, 16, v205
	v_and_b32_e32 v205, 0xffff0000, v205
	v_lshlrev_b32_e32 v210, 16, v206
	v_and_b32_e32 v211, 0xffff0000, v206
	v_lshlrev_b32_e32 v206, 16, v207
	v_and_b32_e32 v207, 0xffff0000, v207
	v_pk_mul_f32 v[130:131], v[130:131], v[204:205]
	v_pk_mul_f32 v[128:129], v[128:129], v[208:209]
	v_pk_mul_f32 v[126:127], v[126:127], v[206:207]
	v_pk_mul_f32 v[124:125], v[124:125], v[210:211]
	s_cbranch_vccnz .LBB0_521
	v_cvt_pk_bf16_f32 v204, v128, v129
	v_cvt_pk_bf16_f32 v205, v130, v131
	v_cvt_pk_bf16_f32 v206, v124, v125
	v_cvt_pk_bf16_f32 v207, v126, v127
	global_store_dwordx4 v[188:189], v[204:207], off
.LBB0_521:
	s_nop 1
	s_waitcnt vmcnt(6)
	v_lshlrev_b32_e32 v204, 16, v156
	v_and_b32_e32 v205, 0xffff0000, v156
	v_lshlrev_b32_e32 v156, 16, v157
	v_and_b32_e32 v157, 0xffff0000, v157
	v_lshlrev_b32_e32 v206, 16, v158
	v_and_b32_e32 v207, 0xffff0000, v158
	v_lshlrev_b32_e32 v158, 16, v159
	v_and_b32_e32 v159, 0xffff0000, v159
	v_pk_mul_f32 v[98:99], v[98:99], v[156:157]
	v_cndmask_b32_e64 v156, 0, 1, s[72:73]
	v_pk_mul_f32 v[96:97], v[96:97], v[204:205]
	v_pk_mul_f32 v[94:95], v[94:95], v[158:159]
	v_cmp_ne_u32_e64 s[38:39], 1, v156
	s_andn2_b64 vcc, exec, s[72:73]
	v_pk_mul_f32 v[92:93], v[92:93], v[206:207]
	s_cbranch_vccnz .LBB0_523
	v_cvt_pk_bf16_f32 v156, v96, v97
	v_cvt_pk_bf16_f32 v157, v98, v99
	v_cvt_pk_bf16_f32 v158, v92, v93
	v_cvt_pk_bf16_f32 v159, v94, v95
	global_store_dwordx4 v[188:189], v[156:159], off offset:256
.LBB0_523:
	v_ashrrev_i32_e32 v187, 31, v186
	s_nop 0
	v_lshlrev_b64 v[156:157], 11, v[186:187]
	s_waitcnt vmcnt(5)
	v_lshlrev_b32_e32 v158, 16, v152
	v_and_b32_e32 v159, 0xffff0000, v152
	v_lshlrev_b32_e32 v152, 16, v153
	v_and_b32_e32 v153, 0xffff0000, v153
	v_lshlrev_b32_e32 v186, 16, v154
	v_and_b32_e32 v187, 0xffff0000, v154
	v_lshlrev_b32_e32 v154, 16, v155
	v_and_b32_e32 v155, 0xffff0000, v155
	v_pk_mul_f32 v[122:123], v[122:123], v[152:153]
	v_lshl_add_u64 v[152:153], s[86:87], 0, v[156:157]
	v_pk_mul_f32 v[120:121], v[120:121], v[158:159]
	v_pk_mul_f32 v[118:119], v[118:119], v[154:155]
	v_pk_mul_f32 v[116:117], v[116:117], v[186:187]
	s_and_b64 vcc, exec, s[38:39]
	v_lshl_add_u64 v[152:153], v[176:177], 1, v[152:153]
	s_cbranch_vccnz .LBB0_525
	v_cvt_pk_bf16_f32 v154, v120, v121
	v_cvt_pk_bf16_f32 v155, v122, v123
	v_cvt_pk_bf16_f32 v156, v116, v117
	v_cvt_pk_bf16_f32 v157, v118, v119
	global_store_dwordx4 v[152:153], v[154:157], off
; __device__ __forceinline__ unsigned cvt_pk_bf16(float lo, float hi) { f32x2c v = {lo, hi}; bf16x2c b = __builtin_convertvector(v, bf16x2c); return __builtin_bit_cast(unsigned, b); }
; __device__ __forceinline__ float bf_lo(unsigned w) { return __uint_as_float(w << 16); }
; __device__ __forceinline__ float bf_hi(unsigned w) { return __uint_as_float(w & 0xffff0000u); }
;     __device__ __forceinline__ void operator()(f32x4 (&acc)[2][2][4][2], const Unit& u, int wr, int wc, int fr, int fq) const {
;     ...
;                 for (int bj = 0; bj < 2; ++bj) ga[m][bj] = *(const u32x4*)(P + (size_t)(row0 + ai * HALF + m * 16) * 3328 + gcol + bj * HALF);
; #pragma unroll
;             for (int m = 0; m < 4; ++m)
; #pragma unroll
;                 for (int bj = 0; bj < 2; ++bj) {
;                     const u32x4 g = ga[m][bj];
;                     const f32x4 a0 = (f32x4){bf_lo(g.x), bf_hi(g.x), bf_lo(g.y), bf_hi(g.y)}, a1 = (f32x4){bf_lo(g.z), bf_hi(g.z), bf_lo(g.w), bf_hi(g.w)};
;                     acc[ai][bj][m][0] *= a0; acc[ai][bj][m][1] *= a1;
;                     if (u.seg != 0) {
;                         const f32x4 v0 = acc[ai][bj][m][0], v1 = acc[ai][bj][m][1];
;                         u32x4 w; w.x = cvt_pk_bf16(v0[0], v0[1]); w.y = cvt_pk_bf16(v0[2], v0[3]); w.z = cvt_pk_bf16(v1[0], v1[1]); w.w = cvt_pk_bf16(v1[2], v1[3]);
;                         *(u32x4*)(O + (size_t)(row0 + ai * HALF + m * 16) * 1024 + col0 + bj * HALF) = w;
;                     }
.LBB0_525:
	s_nop 1
	s_waitcnt vmcnt(4)
	v_lshlrev_b32_e32 v154, 16, v148
	v_and_b32_e32 v155, 0xffff0000, v148
	v_lshlrev_b32_e32 v148, 16, v149
	v_and_b32_e32 v149, 0xffff0000, v149
	v_lshlrev_b32_e32 v156, 16, v150
	v_and_b32_e32 v157, 0xffff0000, v150
	v_lshlrev_b32_e32 v150, 16, v151
	v_and_b32_e32 v151, 0xffff0000, v151
	v_pk_mul_f32 v[90:91], v[90:91], v[148:149]
	v_pk_mul_f32 v[88:89], v[88:89], v[154:155]
	v_pk_mul_f32 v[86:87], v[86:87], v[150:151]
	s_and_b64 vcc, exec, s[38:39]
	v_pk_mul_f32 v[84:85], v[84:85], v[156:157]
	s_cbranch_vccnz .LBB0_527
	v_cvt_pk_bf16_f32 v148, v88, v89
	v_cvt_pk_bf16_f32 v149, v90, v91
	v_cvt_pk_bf16_f32 v150, v84, v85
	v_cvt_pk_bf16_f32 v151, v86, v87
	global_store_dwordx4 v[152:153], v[148:151], off offset:256
.LBB0_527:
	v_ashrrev_i32_e32 v185, 31, v184
	s_nop 0
	v_lshlrev_b64 v[148:149], 11, v[184:185]
	s_waitcnt vmcnt(3)
	v_lshlrev_b32_e32 v150, 16, v144
	v_and_b32_e32 v151, 0xffff0000, v144
	v_lshlrev_b32_e32 v144, 16, v145
	v_and_b32_e32 v145, 0xffff0000, v145
	v_lshlrev_b32_e32 v152, 16, v146
	v_and_b32_e32 v153, 0xffff0000, v146
	v_lshlrev_b32_e32 v146, 16, v147
	v_and_b32_e32 v147, 0xffff0000, v147
	v_pk_mul_f32 v[114:115], v[114:115], v[144:145]
	v_lshl_add_u64 v[144:145], s[86:87], 0, v[148:149]
	v_pk_mul_f32 v[112:113], v[112:113], v[150:151]
	v_pk_mul_f32 v[110:111], v[110:111], v[146:147]
	v_pk_mul_f32 v[108:109], v[108:109], v[152:153]
	s_and_b64 vcc, exec, s[38:39]
	v_lshl_add_u64 v[144:145], v[176:177], 1, v[144:145]
	s_cbranch_vccnz .LBB0_529
	v_cvt_pk_bf16_f32 v146, v112, v113
	v_cvt_pk_bf16_f32 v147, v114, v115
	v_cvt_pk_bf16_f32 v148, v108, v109
	v_cvt_pk_bf16_f32 v149, v110, v111
	global_store_dwordx4 v[144:145], v[146:149], off
.LBB0_529:
	s_nop 1
	s_waitcnt vmcnt(2)
	v_lshlrev_b32_e32 v146, 16, v140
	v_and_b32_e32 v147, 0xffff0000, v140
	v_lshlrev_b32_e32 v140, 16, v141
	v_and_b32_e32 v141, 0xffff0000, v141
	v_lshlrev_b32_e32 v148, 16, v142
	v_and_b32_e32 v149, 0xffff0000, v142
	v_lshlrev_b32_e32 v142, 16, v143
	v_and_b32_e32 v143, 0xffff0000, v143
	v_pk_mul_f32 v[82:83], v[82:83], v[140:141]
	v_pk_mul_f32 v[80:81], v[80:81], v[146:147]
	v_pk_mul_f32 v[78:79], v[78:79], v[142:143]
	s_and_b64 vcc, exec, s[38:39]
	v_pk_mul_f32 v[76:77], v[76:77], v[148:149]
	s_cbranch_vccnz .LBB0_531
	v_cvt_pk_bf16_f32 v140, v80, v81
	v_cvt_pk_bf16_f32 v141, v82, v83
	v_cvt_pk_bf16_f32 v142, v76, v77
	v_cvt_pk_bf16_f32 v143, v78, v79
	global_store_dwordx4 v[144:145], v[140:143], off offset:256
.LBB0_531:
	v_ashrrev_i32_e32 v183, 31, v182
	s_nop 0
	v_lshlrev_b64 v[140:141], 11, v[182:183]
	s_waitcnt vmcnt(1)
	v_lshlrev_b32_e32 v142, 16, v136
	v_and_b32_e32 v143, 0xffff0000, v136
	v_lshlrev_b32_e32 v136, 16, v137
	v_and_b32_e32 v137, 0xffff0000, v137
	v_lshlrev_b32_e32 v144, 16, v138
	v_and_b32_e32 v145, 0xffff0000, v138
	v_lshlrev_b32_e32 v138, 16, v139
	v_and_b32_e32 v139, 0xffff0000, v139
	v_pk_mul_f32 v[106:107], v[106:107], v[136:137]
	v_lshl_add_u64 v[136:137], s[86:87], 0, v[140:141]
	v_pk_mul_f32 v[104:105], v[104:105], v[142:143]
	v_pk_mul_f32 v[102:103], v[102:103], v[138:139]
	v_pk_mul_f32 v[100:101], v[100:101], v[144:145]
	s_and_b64 vcc, exec, s[38:39]
	v_lshl_add_u64 v[136:137], v[176:177], 1, v[136:137]
	s_cbranch_vccnz .LBB0_533
	v_cvt_pk_bf16_f32 v138, v104, v105
	v_cvt_pk_bf16_f32 v139, v106, v107
	v_cvt_pk_bf16_f32 v140, v100, v101
	v_cvt_pk_bf16_f32 v141, v102, v103
	global_store_dwordx4 v[136:137], v[138:141], off
.LBB0_533:
	s_nop 1
	s_waitcnt vmcnt(0)
	v_lshlrev_b32_e32 v138, 16, v132
	v_and_b32_e32 v139, 0xffff0000, v132
	v_lshlrev_b32_e32 v132, 16, v133
	v_and_b32_e32 v133, 0xffff0000, v133
	v_lshlrev_b32_e32 v140, 16, v134
	v_and_b32_e32 v141, 0xffff0000, v134
	v_lshlrev_b32_e32 v134, 16, v135
	v_and_b32_e32 v135, 0xffff0000, v135
	v_pk_mul_f32 v[74:75], v[74:75], v[132:133]
	v_pk_mul_f32 v[72:73], v[72:73], v[138:139]
	v_pk_mul_f32 v[70:71], v[70:71], v[134:135]
	s_and_b64 vcc, exec, s[38:39]
	v_pk_mul_f32 v[68:69], v[68:69], v[140:141]
	s_cbranch_vccnz .LBB0_535
	v_cvt_pk_bf16_f32 v132, v72, v73
	v_cvt_pk_bf16_f32 v133, v74, v75
	v_cvt_pk_bf16_f32 v134, v68, v69
	v_cvt_pk_bf16_f32 v135, v70, v71
	global_store_dwordx4 v[136:137], v[132:135], off offset:256
